# v25: v24 + postproc_b: the 64 LDS weight reads per row issued in two batches of 32 with one wait each (register-renamed chains, same accumulate order)
# speedup vs baseline: 1.0100x; 1.0020x over previous
; #define LAS __attribute__((address_space(3)))
; __device__ __forceinline__ unsigned f2bf(float f) { unsigned u = __builtin_bit_cast(unsigned, f); return (u + 0x7fffu + ((u >> 16) & 1u)) >> 16; }
; __device__ __forceinline__ float silu_f(float g) { return g * __builtin_amdgcn_rcpf(1.0f + fast_exp2(-g * LOG2E)); }
; __device__ __forceinline__ void postproc_b(const Params& p, LAS unsigned char* lds, int l, int gw, int ngw, int lane) {
;     ...
;     for (int r = gw; r < 8192; r += ngw) {
;         const int kv = r >> 12, rr = r & 4095, i = rr & 255;
;         const LAS float* w2 = w2l + kv * 128 * 64 + lane;
;         float hs0 = CMPB[(l * 2 + kv) * 128 + lane], hs1 = CMPB[(l * 2 + kv) * 128 + 64 + lane];
; #pragma unroll
;         for (int sl = 0; sl < 4; ++sl) { hs0 += HIDP[((size_t)sl * 8192 + r) * 128 + lane]; hs1 += HIDP[((size_t)sl * 8192 + r) * 128 + 64 + lane]; }
;         const int h0 = __builtin_bit_cast(int, bf2f(f2bf(silu_f(hs0)))), h1 = __builtin_bit_cast(int, bf2f(f2bf(silu_f(hs1))));
;         float a = 0.f;
; #pragma unroll
;         for (int k = 0; k < 64; ++k) a += __builtin_bit_cast(float, __builtin_amdgcn_readlane(h0, k)) * w2[k * 64];
; #pragma unroll
;         for (int k = 0; k < 64; ++k) a += __builtin_bit_cast(float, __builtin_amdgcn_readlane(h1, k)) * w2[(64 + k) * 64];
.LBB0_623:
	s_ashr_i32 s1, s0, 12
	v_lshl_add_u32 v6, s1, 7, v2
	v_ashrrev_i32_e32 v7, 31, v6
	v_lshl_add_u64 v[6:7], v[6:7], 2, s[16:17]
	global_load_dword v18, v[6:7], off
	global_load_dword v19, v[6:7], off offset:256
	global_load_dword v20, v[4:5], off
	global_load_dword v21, v[4:5], off offset:256
	s_mov_b32 s2, 0x400000
	v_add_co_u32_e32 v6, vcc, s2, v4
	s_nop 1
	v_addc_co_u32_e32 v7, vcc, 0, v5, vcc
	global_load_dword v22, v[6:7], off
	global_load_dword v23, v[6:7], off offset:256
	s_mov_b32 s2, 0x800000
	v_add_co_u32_e32 v6, vcc, s2, v4
	s_nop 1
	v_addc_co_u32_e32 v7, vcc, 0, v5, vcc
	global_load_dword v24, v[6:7], off
	global_load_dword v25, v[6:7], off offset:256
	s_mov_b32 s2, 0xc00000
	v_add_co_u32_e32 v6, vcc, s2, v4
	s_nop 1
	v_addc_co_u32_e32 v7, vcc, 0, v5, vcc
	global_load_dword v26, v[6:7], off
	global_load_dword v27, v[6:7], off offset:256
	s_mov_b64 s[12:13], -1
	v_lshl_add_u32 v7, s1, 15, v3
	ds_read2st64_b32 v[28:29], v7 offset1:1
	ds_read2st64_b32 v[30:31], v7 offset0:2 offset1:3
	ds_read2st64_b32 v[32:33], v7 offset0:4 offset1:5
	ds_read2st64_b32 v[34:35], v7 offset0:6 offset1:7
	ds_read2st64_b32 v[36:37], v7 offset0:8 offset1:9
	ds_read2st64_b32 v[38:39], v7 offset0:10 offset1:11
	ds_read2st64_b32 v[40:41], v7 offset0:12 offset1:13
	ds_read2st64_b32 v[42:43], v7 offset0:14 offset1:15
	ds_read2st64_b32 v[44:45], v7 offset0:16 offset1:17
	ds_read2st64_b32 v[46:47], v7 offset0:18 offset1:19
	ds_read2st64_b32 v[48:49], v7 offset0:20 offset1:21
	ds_read2st64_b32 v[50:51], v7 offset0:22 offset1:23
	ds_read2st64_b32 v[52:53], v7 offset0:24 offset1:25
	ds_read2st64_b32 v[54:55], v7 offset0:26 offset1:27
	ds_read2st64_b32 v[56:57], v7 offset0:28 offset1:29
	ds_read2st64_b32 v[58:59], v7 offset0:30 offset1:31
	ds_read2st64_b32 v[60:61], v7 offset0:32 offset1:33
	ds_read2st64_b32 v[62:63], v7 offset0:34 offset1:35
	ds_read2st64_b32 v[64:65], v7 offset0:36 offset1:37
	ds_read2st64_b32 v[66:67], v7 offset0:38 offset1:39
	ds_read2st64_b32 v[68:69], v7 offset0:40 offset1:41
	ds_read2st64_b32 v[70:71], v7 offset0:42 offset1:43
	ds_read2st64_b32 v[72:73], v7 offset0:44 offset1:45
	ds_read2st64_b32 v[74:75], v7 offset0:46 offset1:47
	ds_read2st64_b32 v[76:77], v7 offset0:48 offset1:49
	ds_read2st64_b32 v[78:79], v7 offset0:50 offset1:51
	ds_read2st64_b32 v[80:81], v7 offset0:52 offset1:53
	ds_read2st64_b32 v[82:83], v7 offset0:54 offset1:55
	ds_read2st64_b32 v[84:85], v7 offset0:56 offset1:57
	ds_read2st64_b32 v[86:87], v7 offset0:58 offset1:59
	ds_read2st64_b32 v[88:89], v7 offset0:60 offset1:61
	ds_read2st64_b32 v[90:91], v7 offset0:62 offset1:63
	s_waitcnt lgkmcnt(0)
	s_waitcnt vmcnt(0)
	v_add_f32_e32 v8, v18, v20
	v_add_f32_e32 v9, v19, v21
	v_add_f32_e32 v8, v8, v22
	v_add_f32_e32 v9, v9, v23
	v_add_f32_e32 v8, v8, v24
	v_add_f32_e32 v9, v9, v25
	v_add_f32_e32 v8, v8, v26
	v_add_f32_e32 v6, v9, v27
	v_mul_f32_e32 v9, 0xbfb8aa3b, v8
	v_exp_f32_e32 v9, v9
	s_nop 0
	v_add_f32_e32 v9, 1.0, v9
	v_rcp_f32_e32 v9, v9
	s_nop 0
	v_mul_f32_e32 v8, v8, v9
	v_bfe_u32 v9, v8, 16, 1
	v_add3_u32 v8, v8, v9, s79
	v_mul_f32_e32 v9, 0xbfb8aa3b, v6
	v_exp_f32_e32 v9, v9
	v_and_b32_e32 v8, 0xffff0000, v8
	v_add_f32_e32 v9, 1.0, v9
	v_rcp_f32_e32 v9, v9
	v_readlane_b32 s1, v8, 0
	v_mul_f32_e32 v6, v6, v9
	v_bfe_u32 v9, v6, 16, 1
	v_add3_u32 v9, v6, v9, s79
	v_fma_f32 v6, v28, s1, 0
	v_readlane_b32 s1, v8, 1
	s_nop 1
	v_fmac_f32_e32 v6, s1, v29
	v_readlane_b32 s1, v8, 2
	s_nop 0
	s_nop 0
	v_fmac_f32_e32 v6, s1, v30
	v_readlane_b32 s1, v8, 3
	s_nop 1
	v_fmac_f32_e32 v6, s1, v31
	v_readlane_b32 s1, v8, 4
	s_nop 0
	s_nop 0
	v_fmac_f32_e32 v6, s1, v32
	v_readlane_b32 s1, v8, 5
	s_nop 1
	v_fmac_f32_e32 v6, s1, v33
	v_readlane_b32 s1, v8, 6
	s_nop 0
	s_nop 0
	v_fmac_f32_e32 v6, s1, v34
	v_readlane_b32 s1, v8, 7
	s_nop 1
	v_fmac_f32_e32 v6, s1, v35
	v_readlane_b32 s1, v8, 8
	s_nop 0
	s_nop 0
	v_fmac_f32_e32 v6, s1, v36
	v_readlane_b32 s1, v8, 9
	s_nop 1
	v_fmac_f32_e32 v6, s1, v37
	v_readlane_b32 s1, v8, 10
	s_nop 0
	s_nop 0
	v_fmac_f32_e32 v6, s1, v38
	v_readlane_b32 s1, v8, 11
	s_nop 1
	v_fmac_f32_e32 v6, s1, v39
	v_readlane_b32 s1, v8, 12
	s_nop 0
	s_nop 0
	v_fmac_f32_e32 v6, s1, v40
	v_readlane_b32 s1, v8, 13
	s_nop 1
	v_fmac_f32_e32 v6, s1, v41
	v_readlane_b32 s1, v8, 14
	s_nop 0
	s_nop 0
	v_fmac_f32_e32 v6, s1, v42
	v_readlane_b32 s1, v8, 15
	s_nop 1
	v_fmac_f32_e32 v6, s1, v43
	v_readlane_b32 s1, v8, 16
	s_nop 0
	s_nop 0
	v_fmac_f32_e32 v6, s1, v44
	v_readlane_b32 s1, v8, 17
	s_nop 1
	v_fmac_f32_e32 v6, s1, v45
	v_readlane_b32 s1, v8, 18
	s_nop 0
	s_nop 0
	v_fmac_f32_e32 v6, s1, v46
	v_readlane_b32 s1, v8, 19
	s_nop 1
	v_fmac_f32_e32 v6, s1, v47
	v_readlane_b32 s1, v8, 20
	s_nop 0
	s_nop 0
	v_fmac_f32_e32 v6, s1, v48
	v_readlane_b32 s1, v8, 21
	s_nop 1
	v_fmac_f32_e32 v6, s1, v49
	v_readlane_b32 s1, v8, 22
	s_nop 0
	s_nop 0
	v_fmac_f32_e32 v6, s1, v50
	v_readlane_b32 s1, v8, 23
	s_nop 1
	v_fmac_f32_e32 v6, s1, v51
	v_readlane_b32 s1, v8, 24
	s_nop 0
	s_nop 0
	v_fmac_f32_e32 v6, s1, v52
	v_readlane_b32 s1, v8, 25
	s_nop 1
	v_fmac_f32_e32 v6, s1, v53
	v_readlane_b32 s1, v8, 26
	s_nop 0
	s_nop 0
	v_fmac_f32_e32 v6, s1, v54
	v_readlane_b32 s1, v8, 27
	s_nop 1
	v_fmac_f32_e32 v6, s1, v55
	v_readlane_b32 s1, v8, 28
	s_nop 0
	s_nop 0
	v_fmac_f32_e32 v6, s1, v56
	v_readlane_b32 s1, v8, 29
	s_nop 1
	v_fmac_f32_e32 v6, s1, v57
	v_readlane_b32 s1, v8, 30
	s_nop 0
	s_nop 0
	v_fmac_f32_e32 v6, s1, v58
	v_readlane_b32 s1, v8, 31
	s_nop 1
	v_fmac_f32_e32 v6, s1, v59
	v_readlane_b32 s1, v8, 32
	s_nop 0
	s_nop 0
	v_fmac_f32_e32 v6, s1, v60
	v_readlane_b32 s1, v8, 33
	s_nop 1
	v_fmac_f32_e32 v6, s1, v61
	v_readlane_b32 s1, v8, 34
	s_nop 0
	s_nop 0
; __device__ __forceinline__ void postproc_b(const Params& p, LAS unsigned char* lds, int l, int gw, int ngw, int lane) {
;     ...
;         for (int k = 0; k < 64; ++k) a += __builtin_bit_cast(float, __builtin_amdgcn_readlane(h0, k)) * w2[k * 64];
; #pragma unroll
;         for (int k = 0; k < 64; ++k) a += __builtin_bit_cast(float, __builtin_amdgcn_readlane(h1, k)) * w2[(64 + k) * 64];
	v_fmac_f32_e32 v6, s1, v62
	v_readlane_b32 s1, v8, 35
	s_nop 1
	v_fmac_f32_e32 v6, s1, v63
	v_readlane_b32 s1, v8, 36
	s_nop 0
	s_nop 0
	v_fmac_f32_e32 v6, s1, v64
	v_readlane_b32 s1, v8, 37
	s_nop 1
	v_fmac_f32_e32 v6, s1, v65
	v_readlane_b32 s1, v8, 38
	s_nop 0
	s_nop 0
	v_fmac_f32_e32 v6, s1, v66
	v_readlane_b32 s1, v8, 39
	s_nop 1
	v_fmac_f32_e32 v6, s1, v67
	v_readlane_b32 s1, v8, 40
	s_nop 0
	s_nop 0
	v_fmac_f32_e32 v6, s1, v68
	v_readlane_b32 s1, v8, 41
	s_nop 1
	v_fmac_f32_e32 v6, s1, v69
	v_readlane_b32 s1, v8, 42
	s_nop 0
	s_nop 0
	v_fmac_f32_e32 v6, s1, v70
	v_readlane_b32 s1, v8, 43
	s_nop 1
	v_fmac_f32_e32 v6, s1, v71
	v_readlane_b32 s1, v8, 44
	s_nop 0
	s_nop 0
	v_fmac_f32_e32 v6, s1, v72
	v_readlane_b32 s1, v8, 45
	s_nop 1
	v_fmac_f32_e32 v6, s1, v73
	v_readlane_b32 s1, v8, 46
	s_nop 0
	s_nop 0
	v_fmac_f32_e32 v6, s1, v74
	v_readlane_b32 s1, v8, 47
	s_nop 1
	v_fmac_f32_e32 v6, s1, v75
	v_readlane_b32 s1, v8, 48
	s_nop 0
	s_nop 0
	v_fmac_f32_e32 v6, s1, v76
	v_readlane_b32 s1, v8, 49
	s_nop 1
	v_fmac_f32_e32 v6, s1, v77
	v_readlane_b32 s1, v8, 50
	s_nop 0
	s_nop 0
	v_fmac_f32_e32 v6, s1, v78
	v_readlane_b32 s1, v8, 51
	s_nop 1
	v_fmac_f32_e32 v6, s1, v79
	v_readlane_b32 s1, v8, 52
	s_nop 0
	s_nop 0
	v_fmac_f32_e32 v6, s1, v80
	v_readlane_b32 s1, v8, 53
	s_nop 1
	v_fmac_f32_e32 v6, s1, v81
	v_readlane_b32 s1, v8, 54
	s_nop 0
	s_nop 0
	v_fmac_f32_e32 v6, s1, v82
	v_readlane_b32 s1, v8, 55
	s_nop 1
	v_fmac_f32_e32 v6, s1, v83
	v_readlane_b32 s1, v8, 56
	s_nop 0
	s_nop 0
	v_fmac_f32_e32 v6, s1, v84
	v_readlane_b32 s1, v8, 57
	s_nop 1
	v_fmac_f32_e32 v6, s1, v85
	v_readlane_b32 s1, v8, 58
	s_nop 0
	s_nop 0
	v_fmac_f32_e32 v6, s1, v86
	v_readlane_b32 s1, v8, 59
	s_nop 1
	v_fmac_f32_e32 v6, s1, v87
	v_readlane_b32 s1, v8, 60
	s_nop 0
	s_nop 0
	v_fmac_f32_e32 v6, s1, v88
	v_readlane_b32 s1, v8, 61
	s_nop 1
	v_fmac_f32_e32 v6, s1, v89
	v_readlane_b32 s1, v8, 62
	s_nop 0
	s_nop 0
	v_fmac_f32_e32 v6, s1, v90
	v_readlane_b32 s1, v8, 63
	v_and_b32_e32 v8, 0xffff0000, v9
	s_nop 0
	v_fmac_f32_e32 v6, s1, v91
	ds_read2st64_b32 v[28:29], v7 offset0:64 offset1:65
	ds_read2st64_b32 v[30:31], v7 offset0:66 offset1:67
	ds_read2st64_b32 v[32:33], v7 offset0:68 offset1:69
	ds_read2st64_b32 v[34:35], v7 offset0:70 offset1:71
	ds_read2st64_b32 v[36:37], v7 offset0:72 offset1:73
	ds_read2st64_b32 v[38:39], v7 offset0:74 offset1:75
	ds_read2st64_b32 v[40:41], v7 offset0:76 offset1:77
	ds_read2st64_b32 v[42:43], v7 offset0:78 offset1:79
	ds_read2st64_b32 v[44:45], v7 offset0:80 offset1:81
	ds_read2st64_b32 v[46:47], v7 offset0:82 offset1:83
	ds_read2st64_b32 v[48:49], v7 offset0:84 offset1:85
	ds_read2st64_b32 v[50:51], v7 offset0:86 offset1:87
	ds_read2st64_b32 v[52:53], v7 offset0:88 offset1:89
	ds_read2st64_b32 v[54:55], v7 offset0:90 offset1:91
	ds_read2st64_b32 v[56:57], v7 offset0:92 offset1:93
	ds_read2st64_b32 v[58:59], v7 offset0:94 offset1:95
	ds_read2st64_b32 v[60:61], v7 offset0:96 offset1:97
	ds_read2st64_b32 v[62:63], v7 offset0:98 offset1:99
	ds_read2st64_b32 v[64:65], v7 offset0:100 offset1:101
	ds_read2st64_b32 v[66:67], v7 offset0:102 offset1:103
	ds_read2st64_b32 v[68:69], v7 offset0:104 offset1:105
	ds_read2st64_b32 v[70:71], v7 offset0:106 offset1:107
	ds_read2st64_b32 v[72:73], v7 offset0:108 offset1:109
	ds_read2st64_b32 v[74:75], v7 offset0:110 offset1:111
	ds_read2st64_b32 v[76:77], v7 offset0:112 offset1:113
	ds_read2st64_b32 v[78:79], v7 offset0:114 offset1:115
	ds_read2st64_b32 v[80:81], v7 offset0:116 offset1:117
	ds_read2st64_b32 v[82:83], v7 offset0:118 offset1:119
	ds_read2st64_b32 v[84:85], v7 offset0:120 offset1:121
	ds_read2st64_b32 v[86:87], v7 offset0:122 offset1:123
	ds_read2st64_b32 v[88:89], v7 offset0:124 offset1:125
	ds_read2st64_b32 v[90:91], v7 offset0:126 offset1:127
	s_waitcnt lgkmcnt(0)
; __device__ __forceinline__ unsigned f2bf(float f) { unsigned u = __builtin_bit_cast(unsigned, f); return (u + 0x7fffu + ((u >> 16) & 1u)) >> 16; }
; __device__ __forceinline__ void postproc_b(const Params& p, LAS unsigned char* lds, int l, int gw, int ngw, int lane) {
;     ...
;         for (int k = 0; k < 64; ++k) a += __builtin_bit_cast(float, __builtin_amdgcn_readlane(h1, k)) * w2[(64 + k) * 64];
;         if (kv == 0) { float y = a * rsqrtf(wave_sum(a * a) * (1.0f / 64) + EPS) * gck; if (i == 255) y = 0.f; KCMP[(size_t)rr * 64 + lane] = (bf16_t)f2bf(y); }
;         else { if (i == 255) a = 0.f; VCMP[(size_t)rr * 64 + lane] = (bf16_t)f2bf(a); }
	v_readlane_b32 s1, v8, 0
	s_nop 0
	s_nop 0
	v_fmac_f32_e32 v6, s1, v28
	v_readlane_b32 s1, v8, 1
	s_nop 1
	v_fmac_f32_e32 v6, s1, v29
	v_readlane_b32 s1, v8, 2
	s_nop 0
	s_nop 0
	v_fmac_f32_e32 v6, s1, v30
	v_readlane_b32 s1, v8, 3
	s_nop 1
	v_fmac_f32_e32 v6, s1, v31
	v_readlane_b32 s1, v8, 4
	s_nop 0
	s_nop 0
	v_fmac_f32_e32 v6, s1, v32
	v_readlane_b32 s1, v8, 5
	s_nop 1
	v_fmac_f32_e32 v6, s1, v33
	v_readlane_b32 s1, v8, 6
	s_nop 0
	s_nop 0
	v_fmac_f32_e32 v6, s1, v34
	v_readlane_b32 s1, v8, 7
	s_nop 1
	v_fmac_f32_e32 v6, s1, v35
	v_readlane_b32 s1, v8, 8
	s_nop 0
	s_nop 0
	v_fmac_f32_e32 v6, s1, v36
	v_readlane_b32 s1, v8, 9
	s_nop 1
	v_fmac_f32_e32 v6, s1, v37
	v_readlane_b32 s1, v8, 10
	s_nop 0
	s_nop 0
	v_fmac_f32_e32 v6, s1, v38
	v_readlane_b32 s1, v8, 11
	s_nop 1
	v_fmac_f32_e32 v6, s1, v39
	v_readlane_b32 s1, v8, 12
	s_nop 0
	s_nop 0
	v_fmac_f32_e32 v6, s1, v40
	v_readlane_b32 s1, v8, 13
	s_nop 1
	v_fmac_f32_e32 v6, s1, v41
	v_readlane_b32 s1, v8, 14
	s_nop 0
	s_nop 0
	v_fmac_f32_e32 v6, s1, v42
	v_readlane_b32 s1, v8, 15
	s_nop 1
	v_fmac_f32_e32 v6, s1, v43
	v_readlane_b32 s1, v8, 16
	s_nop 0
	s_nop 0
	v_fmac_f32_e32 v6, s1, v44
	v_readlane_b32 s1, v8, 17
	s_nop 1
	v_fmac_f32_e32 v6, s1, v45
	v_readlane_b32 s1, v8, 18
	s_nop 0
	s_nop 0
	v_fmac_f32_e32 v6, s1, v46
	v_readlane_b32 s1, v8, 19
	s_nop 1
	v_fmac_f32_e32 v6, s1, v47
	v_readlane_b32 s1, v8, 20
	s_nop 0
	s_nop 0
	v_fmac_f32_e32 v6, s1, v48
	v_readlane_b32 s1, v8, 21
	s_nop 1
	v_fmac_f32_e32 v6, s1, v49
	v_readlane_b32 s1, v8, 22
	s_nop 0
	s_nop 0
	v_fmac_f32_e32 v6, s1, v50
	v_readlane_b32 s1, v8, 23
	s_nop 1
	v_fmac_f32_e32 v6, s1, v51
	v_readlane_b32 s1, v8, 24
	s_nop 0
	s_nop 0
	v_fmac_f32_e32 v6, s1, v52
	v_readlane_b32 s1, v8, 25
	s_nop 1
	v_fmac_f32_e32 v6, s1, v53
	v_readlane_b32 s1, v8, 26
	s_nop 0
	s_nop 0
	v_fmac_f32_e32 v6, s1, v54
	v_readlane_b32 s1, v8, 27
	s_nop 1
	v_fmac_f32_e32 v6, s1, v55
	v_readlane_b32 s1, v8, 28
	s_nop 0
	s_nop 0
	v_fmac_f32_e32 v6, s1, v56
	v_readlane_b32 s1, v8, 29
	s_nop 1
	v_fmac_f32_e32 v6, s1, v57
	v_readlane_b32 s1, v8, 30
	s_nop 0
	s_nop 0
	v_fmac_f32_e32 v6, s1, v58
	v_readlane_b32 s1, v8, 31
	s_nop 1
	v_fmac_f32_e32 v6, s1, v59
	v_readlane_b32 s1, v8, 32
	s_nop 0
	s_nop 0
	v_fmac_f32_e32 v6, s1, v60
	v_readlane_b32 s1, v8, 33
	s_nop 1
	v_fmac_f32_e32 v6, s1, v61
	v_readlane_b32 s1, v8, 34
	s_nop 0
	s_nop 0
	v_fmac_f32_e32 v6, s1, v62
	v_readlane_b32 s1, v8, 35
	s_nop 1
	v_fmac_f32_e32 v6, s1, v63
	v_readlane_b32 s1, v8, 36
	s_nop 0
	s_nop 0
	v_fmac_f32_e32 v6, s1, v64
	v_readlane_b32 s1, v8, 37
	s_nop 1
	v_fmac_f32_e32 v6, s1, v65
	v_readlane_b32 s1, v8, 38
	s_nop 0
	s_nop 0
	v_fmac_f32_e32 v6, s1, v66
	v_readlane_b32 s1, v8, 39
	s_nop 1
	v_fmac_f32_e32 v6, s1, v67
	v_readlane_b32 s1, v8, 40
	s_nop 0
	s_nop 0
	v_fmac_f32_e32 v6, s1, v68
	v_readlane_b32 s1, v8, 41
	s_nop 1
	v_fmac_f32_e32 v6, s1, v69
	v_readlane_b32 s1, v8, 42
	s_nop 0
	s_nop 0
	v_fmac_f32_e32 v6, s1, v70
	v_readlane_b32 s1, v8, 43
	s_nop 1
	v_fmac_f32_e32 v6, s1, v71
	v_readlane_b32 s1, v8, 44
	s_nop 0
	s_nop 0
	v_fmac_f32_e32 v6, s1, v72
	v_readlane_b32 s1, v8, 45
	s_nop 1
	v_fmac_f32_e32 v6, s1, v73
	v_readlane_b32 s1, v8, 46
	s_nop 0
	s_nop 0
	v_fmac_f32_e32 v6, s1, v74
	v_readlane_b32 s1, v8, 47
	s_nop 1
	v_fmac_f32_e32 v6, s1, v75
	v_readlane_b32 s1, v8, 48
	s_nop 0
	s_nop 0
	v_fmac_f32_e32 v6, s1, v76
	v_readlane_b32 s1, v8, 49
	s_nop 1
	v_fmac_f32_e32 v6, s1, v77
	v_readlane_b32 s1, v8, 50
	s_nop 0
	s_nop 0
	v_fmac_f32_e32 v6, s1, v78
	v_readlane_b32 s1, v8, 51
	s_nop 1
	v_fmac_f32_e32 v6, s1, v79
	v_readlane_b32 s1, v8, 52
	s_nop 0
	s_nop 0
	v_fmac_f32_e32 v6, s1, v80
	v_readlane_b32 s1, v8, 53
	s_nop 1
	v_fmac_f32_e32 v6, s1, v81
	v_readlane_b32 s1, v8, 54
	s_nop 0
	s_nop 0
	v_fmac_f32_e32 v6, s1, v82
	v_readlane_b32 s1, v8, 55
	s_nop 1
	v_fmac_f32_e32 v6, s1, v83
	v_readlane_b32 s1, v8, 56
	s_nop 0
	s_nop 0
	v_fmac_f32_e32 v6, s1, v84
	v_readlane_b32 s1, v8, 57
	s_nop 1
	v_fmac_f32_e32 v6, s1, v85
	v_readlane_b32 s1, v8, 58
	s_nop 0
	s_nop 0
	v_fmac_f32_e32 v6, s1, v86
	v_readlane_b32 s1, v8, 59
	s_nop 1
	v_fmac_f32_e32 v6, s1, v87
	v_readlane_b32 s1, v8, 60
	s_nop 0
	s_nop 0
	v_fmac_f32_e32 v6, s1, v88
	v_readlane_b32 s1, v8, 61
	s_nop 1
	v_fmac_f32_e32 v6, s1, v89
	v_readlane_b32 s1, v8, 62
	s_nop 0
	s_nop 0
	v_fmac_f32_e32 v6, s1, v90
	v_readlane_b32 s1, v8, 63
	s_nop 1
	v_fmac_f32_e32 v6, s1, v91
	s_and_b32 s1, s0, 0xff
	s_cmpk_gt_u32 s0, 0xfff
	s_cbranch_scc0 .LBB0_625
	s_cmpk_lg_i32 s1, 0xff
	s_cselect_b64 vcc, -1, 0
	v_cndmask_b32_e32 v7, 0, v6, vcc
	v_bfe_u32 v8, v7, 16, 1
	s_and_b32 s2, s14, 0x3ffc0
	v_add3_u32 v7, v7, v8, s79
	s_mov_b64 s[12:13], 0
	v_mov_b32_e32 v8, s2
